# adds: one-iteration-deeper K/V global prefetch in attention tile loop, causal-mask compares only on diagonal tiles, deferred weight tile read back with ds_read_b64_tr_b16
# speedup vs baseline: 1.0007x; 1.0007x over previous
; __device__ __forceinline__ void deferred_tile(LAS bf16_t* t  , int sidx, int lane) {
;     ...
;     int drow = n0 + lane;
;     if (ilv) { const int c = drow < DFF ? drow : drow - DFF; drow = (c >> 7) * 256 + (c & 127) + (drow < DFF ? 0 : 128); }
;     bf16_t* dp = dst + (size_t)drow * ldd + k0;
; #pragma unroll
;     for (int j = 0; j < 8; ++j) { unsigned w[4];
; #pragma unroll
;         for (int e = 0; e < 4; ++e) { const unsigned lo = t[(j * 8 + 2 * e) * 68 + lane], hi = t[(j * 8 + 2 * e + 1) * 68 + lane]; w[e] = lo | (hi << 16); }
;         *(u32x4*)(dp + j * 8) = (u32x4){w[0], w[1], w[2], w[3]}; }
;     asm volatile("s_waitcnt lgkmcnt(0)" ::: "memory");
.LBB0_1078:
	s_or_b64 exec, exec, s[18:19]
	v_mad_u64_u32 v[26:27], s[2:3], v8, v28, 0
	v_ashrrev_i32_e32 v24, 31, v8
	v_mov_b32_e32 v8, v27
	v_mad_u64_u32 v[28:29], s[2:3], v24, v28, v[8:9]
	v_mov_b32_e32 v27, v28
	v_lshl_add_u64 v[22:23], v[26:27], 1, v[22:23]
	v_lshlrev_b32_e32 v8, 1, v25
	v_lshl_add_u64 v[22:23], v[22:23], 0, v[8:9]
	v_lshlrev_b32_e32 v24, 1, v206
	v_sub_u32_e32 v8, v208, v24
	v_bfe_u32 v25, v206, 2, 2
	v_lshl_add_u32 v8, v25, 7, v8
	v_lshl_add_u32 v8, v25, 3, v8
	v_lshrrev_b32_e32 v25, 4, v206
	v_lshl_add_u32 v8, v25, 5, v8
	v_and_b32_e32 v25, 3, v206
	v_lshl_add_u32 v8, v25, 3, v8
	ds_read_b64_tr_b16 v[24:25], v8
	ds_read_b64_tr_b16 v[26:27], v8 offset:544
	s_waitcnt lgkmcnt(0)
	global_store_dwordx4 v[22:23], v[24:27], off
	s_nop 1
	ds_read_b64_tr_b16 v[24:25], v8 offset:1088
	ds_read_b64_tr_b16 v[26:27], v8 offset:1632
	s_waitcnt lgkmcnt(0)
	global_store_dwordx4 v[22:23], v[24:27], off offset:16
	s_nop 1
	ds_read_b64_tr_b16 v[24:25], v8 offset:2176
	ds_read_b64_tr_b16 v[26:27], v8 offset:2720
	s_waitcnt lgkmcnt(0)
	global_store_dwordx4 v[22:23], v[24:27], off offset:32
	s_nop 1
	ds_read_b64_tr_b16 v[24:25], v8 offset:3264
	ds_read_b64_tr_b16 v[26:27], v8 offset:3808
	s_waitcnt lgkmcnt(0)
	global_store_dwordx4 v[22:23], v[24:27], off offset:48
	s_nop 1
	ds_read_b64_tr_b16 v[24:25], v8 offset:4352
	ds_read_b64_tr_b16 v[26:27], v8 offset:4896
	s_waitcnt lgkmcnt(0)
	global_store_dwordx4 v[22:23], v[24:27], off offset:64
	s_nop 1
	ds_read_b64_tr_b16 v[24:25], v8 offset:5440
	ds_read_b64_tr_b16 v[26:27], v8 offset:5984
	s_waitcnt lgkmcnt(0)
	global_store_dwordx4 v[22:23], v[24:27], off offset:80
	s_nop 1
	ds_read_b64_tr_b16 v[24:25], v8 offset:6528
	ds_read_b64_tr_b16 v[26:27], v8 offset:7072
	s_waitcnt lgkmcnt(0)
	global_store_dwordx4 v[22:23], v[24:27], off offset:96
	s_nop 1
	ds_read_b64_tr_b16 v[24:25], v8 offset:7616
	ds_read_b64_tr_b16 v[26:27], v8 offset:8160
	s_waitcnt lgkmcnt(0)
	global_store_dwordx4 v[22:23], v[24:27], off offset:112
	s_nop 1
	s_waitcnt lgkmcnt(0)

; #define LAS __attribute__((address_space(3)))
; #define ATT_LOAD(KR, VR, TI) do { const int t2_ = (TI), bi2_ = t2_ >> 2, kt2_ = t2_ & 3; const int blk2_ = (bi2_ == 0) ? j : bi2_ - 1; const size_t kr_ = rowb + blk2_ * 256 + kt2_ * 64; \
;         KR = *(const u32x4*)(z + (kr_ + skey) * 5120 + 1024 + h * 64 + schunk * 8); VR = *(const u32x4*)(z + (kr_ + vkey) * 5120 + 2048 + h * 64 + vchunk * 8); } while (0)
; __device__ __forceinline__ void attn_item(LAS unsigned char* lds, const bf16_t* z, const float* kmean, bf16_t* cat, int b, int h, int j) {
;     ...
;     for (int ti = 0; ti < ntile; ++ti) {
;         const int bi = ti >> 2, kt = ti & 3; const int blk = (bi == 0) ? j : bi - 1; const bool own = (bi == 0);
;         LAS bf16_t* Ks = KV + (ti & 1) * 2 * 64 * 72; LAS bf16_t* Vt = Ks + 64 * 72;
;         if (ti + 1 < ntile) { ATT_STORE((ti + 1) & 1, kreg, vreg); kreg = kreg2; vreg = vreg2; if (ti + 3 < ntile) ATT_LOAD(kreg2, vreg2, ti + 3); }
.LBB0_1590:
	s_and_b32 s2, s43, 0x80
	s_mulk_i32 s2, 0x90
	s_add_i32 s38, s2, 0
	v_add3_u32 v74, s38, v118, v8
	s_add_i32 s2, s45, 3
	ds_write_b128 v74, v[62:65]
	v_add3_u32 v62, s38, v119, v120
	s_cmp_ge_u32 s2, s42
	ds_write_b16 v62, v58 offset:9216
	ds_write_b16_d16_hi v62, v58 offset:9360
	ds_write_b16 v62, v59 offset:9504
	ds_write_b16_d16_hi v62, v59 offset:9648
	ds_write_b16 v62, v60 offset:9792
	ds_write_b16_d16_hi v62, v60 offset:9936
	ds_write_b16 v62, v61 offset:10080
	ds_write_b16_d16_hi v62, v61 offset:10224
	s_cbranch_scc1 .LBB0_1592
	s_and_b32 s2, s44, 0x7fffff00
	s_addk_i32 s2, 0xff00
	s_ashr_i32 s3, s2, 31
	s_add_u32 s2, s58, s2
	s_addc_u32 s3, s59, s3
	s_and_b32 s8, s44, 0xc0
	s_or_b32 s2, s2, s8
	v_lshl_add_u64 v[58:59], s[2:3], 0, v[102:103]
	v_mad_u64_u32 v[60:61], s[8:9], v58, s77, v[112:113]
	v_mad_i32_i24 v61, v59, s77, v61
	v_or_b32_e32 v62, s2, v117
	v_mov_b64_e32 v[58:59], s[92:93]
	v_mad_u64_u32 v[58:59], s[8:9], v62, s77, v[58:59]
	v_mad_i32_i24 v59, s3, v236, v59
	v_lshl_add_u64 v[58:59], v[58:59], 0, s[56:57]
	v_lshl_add_u64 v[58:59], v[104:105], 1, v[58:59]
	v_add_co_u32_e32 v58, vcc, 0x1000, v58
	s_nop 1
	v_addc_co_u32_e32 v59, vcc, 0, v59, vcc
	s_bitcmp1_b32 s45, 0
	s_cbranch_scc0 .Lmy_ld_even
	global_load_dwordx4 v[66:69], v[60:61], off offset:2048
	global_load_dwordx4 v[70:73], v[58:59], off
	s_branch .LBB0_1592
.Lmy_ld_even:
	global_load_dwordx4 v[54:57], v[60:61], off offset:2048
	global_load_dwordx4 v[50:53], v[58:59], off

; #define LAS __attribute__((address_space(3)))
; __device__ __forceinline__ void attn_item(LAS unsigned char* lds, const bf16_t* z, const float* kmean, bf16_t* cat, int b, int h, int j) {
;     ...
;             for (int ks = 0; ks < 4; ++ks) {
;                 const bf16x8 k0 = *(const LAS bf16x8*)(Ks + (ks * 16 + lq) * 72 + quad * 8), k1 = *(const LAS bf16x8*)(Ks + (ks * 16 + lq) * 72 + 32 + quad * 8);
; #pragma unroll
;                 for (int qg = 0; qg < 2; ++qg) { f32x4 a = (f32x4){0.f, 0.f, 0.f, 0.f};
;                     a = __builtin_amdgcn_mfma_f32_16x16x32_bf16(k0, Qf[qg][0], a, 0, 0, 0);
;                     a = __builtin_amdgcn_mfma_f32_16x16x32_bf16(k1, Qf[qg][1], a, 0, 0, 0);
;                     s[ks][qg] = a; } }
;             bf16x8 Pf[2][2];
;             const bool diag = own && (kt * 64 + 63 > wave * 32);
; #pragma unroll
;             for (int qg = 0; qg < 2; ++qg) {
;                 const int qpos = wave * 32 + qg * 16 + lq; const bool selq = own || (((selm[qg] >> blk) & 1) != 0);
;                 if (diag) {
; #pragma unroll
;                     for (int ks = 0; ks < 4; ++ks)
; #pragma unroll
;                         for (int i = 0; i < 4; ++i) { const int kpos = kt * 64 + ks * 16 + quad * 4 + i; s[ks][qg][i] = (kpos <= qpos) ? s[ks][qg][i] : -INFINITY; }
;                 }
.LBB0_1597:
	s_add_i32 s2, s43, 0xffffff80
	s_and_b32 s2, s2, 0x80
	s_mulk_i32 s2, 0x90
	s_add_i32 s2, s2, 0
	v_add3_u32 v131, s2, v124, v122
	v_add3_u32 v130, s2, v125, v122
	v_add3_u32 v129, s2, v123, v122
	v_add_u32_e32 v128, s2, v121
	v_add_u32_e32 v94, v128, v122
	ds_read_b128 v[154:157], v131
	ds_read_b128 v[158:161], v131 offset:64
	ds_read_b128 v[162:165], v130
	ds_read_b128 v[166:169], v130 offset:64
	ds_read_b128 v[170:173], v129
	ds_read_b128 v[174:177], v129 offset:64
	ds_read_b128 v[178:181], v94
	ds_read_b128 v[182:185], v94 offset:64
	s_waitcnt lgkmcnt(7)
	v_mfma_f32_16x16x32_bf16 v[74:77], v[154:157], v[10:13], 0
	s_add_i32 s2, s44, 0xffffff7f
	s_cmp_gt_i32 s2, s81
	v_mfma_f32_16x16x32_bf16 v[58:61], v[154:157], v[18:21], 0
	s_cselect_b64 s[2:3], -1, 0
	s_and_b64 s[2:3], s[36:37], s[2:3]
	v_add_u32_e32 v114, s44, v99
	s_waitcnt lgkmcnt(6)
	v_mfma_f32_16x16x32_bf16 v[82:85], v[158:161], v[14:17], v[74:77]
	v_mfma_f32_16x16x32_bf16 v[78:81], v[158:161], v[22:25], v[58:61]
	s_waitcnt lgkmcnt(5)
	v_mfma_f32_16x16x32_bf16 v[74:77], v[162:165], v[10:13], 0
	s_andn2_b64 vcc, exec, s[2:3]
	v_mfma_f32_16x16x32_bf16 v[58:61], v[162:165], v[18:21], 0
	s_waitcnt lgkmcnt(4)
	v_mfma_f32_16x16x32_bf16 v[86:89], v[166:169], v[14:17], v[74:77]
	v_mfma_f32_16x16x32_bf16 v[62:65], v[166:169], v[22:25], v[58:61]
	s_waitcnt lgkmcnt(3)
	v_mfma_f32_16x16x32_bf16 v[90:93], v[170:173], v[10:13], 0
	v_mfma_f32_16x16x32_bf16 v[58:61], v[170:173], v[18:21], 0
	s_waitcnt lgkmcnt(2)
	v_mfma_f32_16x16x32_bf16 v[90:93], v[174:177], v[14:17], v[90:93]
	v_mfma_f32_16x16x32_bf16 v[58:61], v[174:177], v[22:25], v[58:61]
	s_waitcnt lgkmcnt(1)
	v_mfma_f32_16x16x32_bf16 v[94:97], v[178:181], v[10:13], 0
	v_mfma_f32_16x16x32_bf16 v[74:77], v[178:181], v[18:21], 0
	s_waitcnt lgkmcnt(0)
	v_mfma_f32_16x16x32_bf16 v[94:97], v[182:185], v[14:17], v[94:97]
	v_mfma_f32_16x16x32_bf16 v[74:77], v[182:185], v[22:25], v[74:77]
	v_add_u32_e32 v190, v131, v101
	v_add_u32_e32 v191, v130, v101
	v_add_u32_e32 v200, v129, v101
	v_lshl_add_u32 v201, v99, 1, v128
	v_add_u32_e32 v190, 0x2000, v190
	v_add_u32_e32 v191, 0x2000, v191
	v_add_u32_e32 v200, 0x2000, v200
	v_add_u32_e32 v201, 0x2000, v201
	ds_read2_b64 v[154:157], v190 offset0:128 offset1:132
	ds_read2_b64 v[158:161], v190 offset0:136 offset1:140
	ds_read2_b64 v[162:165], v191 offset0:128 offset1:132
	ds_read2_b64 v[166:169], v191 offset0:136 offset1:140
	ds_read2_b64 v[170:173], v200 offset0:128 offset1:132
	ds_read2_b64 v[174:177], v200 offset0:136 offset1:140
	ds_read2_b64 v[178:181], v201 offset0:128 offset1:132
	ds_read2_b64 v[182:185], v201 offset0:136 offset1:140
	v_cndmask_b32_e64 v132, 0, 1, s[2:3]
	v_cmp_ne_u32_e64 s[8:9], 1, v132
	s_cbranch_vccnz .LBB0_1599
	v_add_u32_e32 v115, 0xffffff40, v114
	v_add_u32_e32 v136, 0xffffff43, v114
	v_add_u32_e32 v139, 0xffffff52, v114
	v_add_u32_e32 v137, 0xffffff53, v114
	v_add_u32_e32 v141, 0xffffff61, v114
	v_add_u32_e32 v140, 0xffffff62, v114
	v_add_u32_e32 v138, 0xffffff63, v114
	v_cmp_le_i32_e64 s[10:11], v115, v98
	v_cmp_lt_i32_e64 s[12:13], v115, v98
	v_cmp_le_i32_e64 s[16:17], v136, v98
	v_cmp_le_i32_e64 s[22:23], v139, v98
	v_cmp_le_i32_e64 s[24:25], v137, v98
	v_cmp_le_i32_e64 s[28:29], v141, v98
	v_cmp_le_i32_e64 s[30:31], v140, v98
	v_cmp_le_i32_e64 s[34:35], v138, v98
	v_add_u32_e32 v132, 0xffffff42, v114
	v_add_u32_e32 v134, 0xffffff50, v114
	v_add_u32_e32 v133, 0xffffff51, v114
	v_add_u32_e32 v135, 0xffffff60, v114
	v_cmp_le_i32_e64 s[14:15], v132, v98
	v_cmp_le_i32_e64 s[18:19], v134, v98
	v_cmp_le_i32_e64 s[20:21], v133, v98
	v_cmp_le_i32_e64 s[26:27], v135, v98
	s_nop 1
	v_add_u32_e32 v142, 0xffffff70, v114
	v_cmp_le_i32_e32 vcc, v142, v98
	v_add_u32_e32 v142, 0xffffff71, v114
	v_cndmask_b32_e64 v82, v237, v82, s[10:11]
	v_cndmask_b32_e32 v94, v237, v94, vcc
	v_cmp_le_i32_e32 vcc, v142, v98
	v_add_u32_e32 v142, 0xffffff72, v114
	v_add_u32_e32 v114, 0xffffff73, v114
	v_cndmask_b32_e32 v95, v237, v95, vcc
	v_cmp_le_i32_e32 vcc, v142, v98
	v_cndmask_b32_e64 v83, v237, v83, s[12:13]
	v_cndmask_b32_e64 v84, v237, v84, s[14:15]
	v_cndmask_b32_e32 v96, v237, v96, vcc
	v_cmp_le_i32_e32 vcc, v114, v98
	v_cndmask_b32_e64 v85, v237, v85, s[16:17]
	v_cndmask_b32_e64 v86, v237, v86, s[18:19]
	v_cndmask_b32_e64 v87, v237, v87, s[20:21]
	v_cndmask_b32_e64 v88, v237, v88, s[22:23]
	v_cndmask_b32_e64 v89, v237, v89, s[24:25]
	v_cndmask_b32_e64 v90, v237, v90, s[26:27]
	v_cndmask_b32_e64 v91, v237, v91, s[28:29]
	v_cndmask_b32_e64 v92, v237, v92, s[30:31]
	v_cndmask_b32_e64 v93, v237, v93, s[34:35]
	v_cndmask_b32_e32 v97, v237, v97, vcc

; #define LAS __attribute__((address_space(3)))
; #define ATT_LOAD(KR, VR, TI) do { const int t2_ = (TI), bi2_ = t2_ >> 2, kt2_ = t2_ & 3; const int blk2_ = (bi2_ == 0) ? j : bi2_ - 1; const size_t kr_ = rowb + blk2_ * 256 + kt2_ * 64; \
;         KR = *(const u32x4*)(z + (kr_ + skey) * 5120 + 1024 + h * 64 + schunk * 8); VR = *(const u32x4*)(z + (kr_ + vkey) * 5120 + 2048 + h * 64 + vchunk * 8); } while (0)
; __device__ __forceinline__ void attn_item(LAS unsigned char* lds, const bf16_t* z, const float* kmean, bf16_t* cat, int b, int h, int j) {
;     ...
;     for (int ti = 0; ti < ntile; ++ti) {
;         const int bi = ti >> 2, kt = ti & 3; const int blk = (bi == 0) ? j : bi - 1; const bool own = (bi == 0);
;         LAS bf16_t* Ks = KV + (ti & 1) * 2 * 64 * 72; LAS bf16_t* Vt = Ks + 64 * 72;
;         if (ti + 1 < ntile) { ATT_STORE((ti + 1) & 1, kreg, vreg); kreg = kreg2; vreg = vreg2; if (ti + 3 < ntile) ATT_LOAD(kreg2, vreg2, ti + 3); }
;     ...
;         __syncthreads();
;     }
.LBB0_1606:
	s_add_i32 s10, s45, 1
	s_add_i32 s44, s44, 64
	s_addk_i32 s43, 0x80
	s_cmp_lg_u32 s45, s41
	s_waitcnt lgkmcnt(0)
	s_barrier
	s_cbranch_scc0 .LBB0_1608
	s_add_i32 s2, s45, 3
	s_cmp_ge_u32 s2, s42
	s_cbranch_scc1 .Lmy_w0
	s_waitcnt vmcnt(2)
	s_branch .Lmy_cp

; #define LAS __attribute__((address_space(3)))
; #define ATT_LOAD(KR, VR, TI) do { const int t2_ = (TI), bi2_ = t2_ >> 2, kt2_ = t2_ & 3; const int blk2_ = (bi2_ == 0) ? j : bi2_ - 1; const size_t kr_ = rowb + blk2_ * 256 + kt2_ * 64; \
;         KR = *(const u32x4*)(z + (kr_ + skey) * 5120 + 1024 + h * 64 + schunk * 8); VR = *(const u32x4*)(z + (kr_ + vkey) * 5120 + 2048 + h * 64 + vchunk * 8); } while (0)
; __device__ __forceinline__ void attn_item(LAS unsigned char* lds, const bf16_t* z, const float* kmean, bf16_t* cat, int b, int h, int j) {
;     ...
;     for (int ti = 0; ti < ntile; ++ti) {
;         const int bi = ti >> 2, kt = ti & 3; const int blk = (bi == 0) ? j : bi - 1; const bool own = (bi == 0);
;         LAS bf16_t* Ks = KV + (ti & 1) * 2 * 64 * 72; LAS bf16_t* Vt = Ks + 64 * 72;
;         if (ti + 1 < ntile) { ATT_STORE((ti + 1) & 1, kreg, vreg); kreg = kreg2; vreg = vreg2; if (ti + 3 < ntile) ATT_LOAD(kreg2, vreg2, ti + 3); }
.Lmy_cp:
	s_bitcmp1_b32 s45, 0
	s_cbranch_scc0 .Lmy_cp_even
	v_mov_b64_e32 v[64:65], v[56:57]
	v_mov_b64_e32 v[60:61], v[52:53]
	v_mov_b64_e32 v[62:63], v[54:55]
	v_mov_b64_e32 v[58:59], v[50:51]
	s_branch .Lmy_cp_done
.Lmy_cp_even:
	v_mov_b64_e32 v[62:63], v[66:67]
	v_mov_b64_e32 v[64:65], v[68:69]
	v_mov_b64_e32 v[58:59], v[70:71]
	v_mov_b64_e32 v[60:61], v[72:73]
.Lmy_cp_done:
	s_mov_b32 s45, s10
	s_branch .LBB0_1590
